# input-projection epilogue: the 8 rstd loads issued right after the K loop, before the leading half's alignment barrier (FFN2-in epilogue batching kept)
# speedup vs baseline: 1.0192x; 1.0022x over previous
; #define PG8_STAGE(bufoff, gbase, voff) do { _Pragma("unroll") for (int _i = 0; _i < 2; ++_i) \
;         __builtin_amdgcn_global_load_lds((const unsigned*)((const char*)(gbase) + (voff)[_i]), (PG8_LAS unsigned*)(lds + (bufoff) + ldsw + _i * 8192), 16, 0, 0); } while (0)
; #define PG8_LDA(dst, b, h) do { _Pragma("unroll") for (int m = 0; m < 4; ++m) _Pragma("unroll") for (int k = 0; k < 2; ++k) dst[m][k] = *(const PG8_LAS bf16x8*)(lds + PG8_SA(b, h) + aoff + m * 2048 + k * 1024); } while (0)
; #define PG8_LDB(dst, b, h) do { _Pragma("unroll") for (int n = 0; n < 2; ++n) _Pragma("unroll") for (int k = 0; k < 2; ++k) dst[n][k] = *(const PG8_LAS bf16x8*)(lds + PG8_SB(b, h) + boff + n * 2048 + k * 1024); } while (0)
; #define PG8_MMA(ai, bj, At, Bt) do { __builtin_amdgcn_s_setprio(1); _Pragma("unroll") for (int m = 0; m < 4; ++m) _Pragma("unroll") for (int n = 0; n < 2; ++n) _Pragma("unroll") for (int k = 0; k < 2; ++k) \
;         acc[ai][bj][m][n] = __builtin_amdgcn_mfma_f32_16x16x32_bf16(Bt[n][k], At[m][k], acc[ai][bj][m][n], 0, 0, 0); __builtin_amdgcn_s_setprio(0); } while (0)
; #define PG8_WAIT_V(n) asm volatile("s_waitcnt vmcnt(" #n ")" ::: "memory")
; #define PG8_WAIT_L(n) asm volatile("s_waitcnt lgkmcnt(" #n ")" ::: "memory")
; #define PG8_BAR __builtin_amdgcn_s_barrier()
; #define PG8_SCHED __builtin_amdgcn_sched_barrier(0)
; template <class Epi, class Sched, bool ALIGN_EPI = false, bool SP2 = false>
; __device__ __forceinline__ void gemm_phase(PG8_LAS unsigned char* lds, const Gemm g, const Sched& S, const Epi& E, const int tid_arg) {
;     ...
;             PG8_LDB(B0, 0, 0); PG8_LDB(B1, 0, 1); PG8_SCHED; PG8_LDA(At, 0, 0); PG8_STAGE(PG8_SA(1, 1), a1 + hstep, voffA);
;             PG8_WAIT_V(8); PG8_WAIT_L(0); PG8_BAR; PG8_MMA(0, 0, At, B0); PG8_MMA(0, 1, At, B1); PG8_BAR; PG8_SCHED;
;             PG8_LDA(At, 0, 1); PG8_STAGE(PG8_SB(0, 0), b2, voffB); PG8_STAGE(PG8_SB(0, 1), b2 + hstep, voffB); PG8_STAGE(PG8_SA(0, 0), a2, voffA);
;             PG8_WAIT_V(8); PG8_WAIT_L(0); PG8_BAR; PG8_MMA(1, 0, At, B0); PG8_MMA(1, 1, At, B1); PG8_BAR; PG8_SCHED;
.LBB0_363:
	s_add_u32 s36, s14, 0xfffc0080
	s_addc_u32 s37, s15, -1
	s_add_i32 s41, 0, 0x10000
	s_cmp_eq_u32 s40, 12
	s_cselect_b32 s39, s6, s37
	s_cselect_b32 s38, s7, s36
	v_add_u32_e32 v2, s41, v167
	s_cselect_b32 s37, s11, s29
	s_cselect_b32 s36, s13, s27
	s_add_i32 s64, 0, 0x14000
	ds_read_b128 v[156:159], v2
	ds_read_b128 v[160:163], v2 offset:1024
	ds_read_b128 v[170:173], v2 offset:2048
	ds_read_b128 v[174:177], v2 offset:3072
	v_add_u32_e32 v2, s64, v167
	ds_read_b128 v[182:185], v2
	ds_read_b128 v[186:189], v2 offset:1024
	ds_read_b128 v[190:193], v2 offset:2048
	ds_read_b128 v[210:213], v2 offset:3072
	v_lshl_add_u64 v[164:165], s[14:15], 0, v[150:151]
	s_add_i32 m0, s55, 0xc000
	ds_read_b128 v[214:217], v169
	ds_read_b128 v[218:221], v169 offset:1024
	ds_read_b128 v[222:225], v169 offset:2048
	ds_read_b128 v[226:229], v169 offset:3072
	ds_read_b128 v[230:233], v169 offset:4096
	ds_read_b128 v[234:237], v169 offset:5120
	ds_read_b128 v[238:241], v169 offset:6144
	ds_read_b128 v[242:245], v169 offset:7168
	global_load_lds_dwordx4 v[164:165], off
	v_lshl_add_u64 v[164:165], s[14:15], 0, v[152:153]
	s_add_i32 m0, s55, 0xe000
	s_nop 0
	global_load_lds_dwordx4 v[164:165], off
	s_waitcnt vmcnt(8)
	s_waitcnt lgkmcnt(0)
	s_barrier
	s_setprio 1
	s_waitcnt lgkmcnt(0)
	v_mfma_f32_16x16x32_bf16 v[128:131], v[156:159], v[214:217], v[128:131]
	v_mfma_f32_16x16x32_bf16 v[124:127], v[170:173], v[214:217], v[124:127]
	v_mfma_f32_16x16x32_bf16 v[112:115], v[156:159], v[222:225], v[112:115]
	v_mfma_f32_16x16x32_bf16 v[108:111], v[170:173], v[222:225], v[108:111]
	v_mfma_f32_16x16x32_bf16 v[96:99], v[156:159], v[230:233], v[96:99]
	v_mfma_f32_16x16x32_bf16 v[92:95], v[170:173], v[230:233], v[92:95]
	v_mfma_f32_16x16x32_bf16 v[80:83], v[156:159], v[238:241], v[80:83]
	v_mfma_f32_16x16x32_bf16 v[76:79], v[170:173], v[238:241], v[76:79]
	v_mfma_f32_16x16x32_bf16 v[128:131], v[160:163], v[218:221], v[128:131]
	v_mfma_f32_16x16x32_bf16 v[124:127], v[174:177], v[218:221], v[124:127]
	v_mfma_f32_16x16x32_bf16 v[112:115], v[160:163], v[226:229], v[112:115]
	v_mfma_f32_16x16x32_bf16 v[108:111], v[174:177], v[226:229], v[108:111]
	v_mfma_f32_16x16x32_bf16 v[96:99], v[160:163], v[234:237], v[96:99]
	v_mfma_f32_16x16x32_bf16 v[92:95], v[174:177], v[234:237], v[92:95]
	v_mfma_f32_16x16x32_bf16 v[80:83], v[160:163], v[242:245], v[80:83]
	v_mfma_f32_16x16x32_bf16 v[76:79], v[174:177], v[242:245], v[76:79]
	s_setprio 0
	s_setprio 1
	v_mfma_f32_16x16x32_bf16 v[120:123], v[182:185], v[214:217], v[120:123]
	v_mfma_f32_16x16x32_bf16 v[116:119], v[190:193], v[214:217], v[116:119]
	v_mfma_f32_16x16x32_bf16 v[104:107], v[182:185], v[222:225], v[104:107]
	v_mfma_f32_16x16x32_bf16 v[100:103], v[190:193], v[222:225], v[100:103]
	v_mfma_f32_16x16x32_bf16 v[88:91], v[182:185], v[230:233], v[88:91]
	v_mfma_f32_16x16x32_bf16 v[84:87], v[190:193], v[230:233], v[84:87]
	v_mfma_f32_16x16x32_bf16 v[72:75], v[182:185], v[238:241], v[72:75]
	v_mfma_f32_16x16x32_bf16 v[68:71], v[190:193], v[238:241], v[68:71]
	v_mfma_f32_16x16x32_bf16 v[120:123], v[186:189], v[218:221], v[120:123]
	v_mfma_f32_16x16x32_bf16 v[116:119], v[210:213], v[218:221], v[116:119]
	v_mfma_f32_16x16x32_bf16 v[104:107], v[186:189], v[226:229], v[104:107]
	v_mfma_f32_16x16x32_bf16 v[100:103], v[210:213], v[226:229], v[100:103]
	v_mfma_f32_16x16x32_bf16 v[88:91], v[186:189], v[234:237], v[88:91]
	v_mfma_f32_16x16x32_bf16 v[84:87], v[210:213], v[234:237], v[84:87]
	v_mfma_f32_16x16x32_bf16 v[72:75], v[186:189], v[242:245], v[72:75]
	v_mfma_f32_16x16x32_bf16 v[68:71], v[210:213], v[242:245], v[68:71]
	s_setprio 0
	s_barrier
	s_add_i32 s41, s41, s54
	v_lshl_add_u64 v[164:165], s[36:37], 0, v[134:135]
	s_mov_b32 m0, s41
	ds_read_b128 v[214:217], v169 offset:16384
	ds_read_b128 v[218:221], v169 offset:17408
	ds_read_b128 v[222:225], v169 offset:18432
	ds_read_b128 v[226:229], v169 offset:19456
	ds_read_b128 v[230:233], v169 offset:20480
	ds_read_b128 v[234:237], v169 offset:21504
	ds_read_b128 v[238:241], v169 offset:22528
	ds_read_b128 v[242:245], v169 offset:23552
	global_load_lds_dwordx4 v[164:165], off
	s_add_i32 m0, s41, 0x2000
	s_add_u32 s42, s36, 0x40000
	v_lshl_add_u64 v[178:179], s[36:37], 0, v[138:139]
	s_addc_u32 s43, s37, 0
	s_add_i32 s41, s64, s54
	global_load_lds_dwordx4 v[178:179], off
	v_lshl_add_u64 v[194:195], s[42:43], 0, v[134:135]
	s_mov_b32 m0, s41
	v_lshl_add_u64 v[246:247], s[38:39], 0, v[136:137]
	global_load_lds_dwordx4 v[194:195], off
	v_lshl_add_u64 v[194:195], s[42:43], 0, v[138:139]
	s_add_i32 m0, s41, 0x2000
	s_nop 0
	global_load_lds_dwordx4 v[194:195], off
	v_lshl_add_u64 v[194:195], s[38:39], 0, v[132:133]
	s_mov_b32 m0, s55
	s_nop 0
	global_load_lds_dwordx4 v[194:195], off
	s_mov_b32 m0, s56
	s_nop 0
	global_load_lds_dwordx4 v[246:247], off
	s_waitcnt vmcnt(8)
	s_waitcnt lgkmcnt(0)
	s_barrier
; #define PG8_STAGE(bufoff, gbase, voff) do { _Pragma("unroll") for (int _i = 0; _i < 2; ++_i) \
;         __builtin_amdgcn_global_load_lds((const unsigned*)((const char*)(gbase) + (voff)[_i]), (PG8_LAS unsigned*)(lds + (bufoff) + ldsw + _i * 8192), 16, 0, 0); } while (0)
; #define PG8_LDA(dst, b, h) do { _Pragma("unroll") for (int m = 0; m < 4; ++m) _Pragma("unroll") for (int k = 0; k < 2; ++k) dst[m][k] = *(const PG8_LAS bf16x8*)(lds + PG8_SA(b, h) + aoff + m * 2048 + k * 1024); } while (0)
; #define PG8_LDB(dst, b, h) do { _Pragma("unroll") for (int n = 0; n < 2; ++n) _Pragma("unroll") for (int k = 0; k < 2; ++k) dst[n][k] = *(const PG8_LAS bf16x8*)(lds + PG8_SB(b, h) + boff + n * 2048 + k * 1024); } while (0)
; #define PG8_MMA(ai, bj, At, Bt) do { __builtin_amdgcn_s_setprio(1); _Pragma("unroll") for (int m = 0; m < 4; ++m) _Pragma("unroll") for (int n = 0; n < 2; ++n) _Pragma("unroll") for (int k = 0; k < 2; ++k) \
;         acc[ai][bj][m][n] = __builtin_amdgcn_mfma_f32_16x16x32_bf16(Bt[n][k], At[m][k], acc[ai][bj][m][n], 0, 0, 0); __builtin_amdgcn_s_setprio(0); } while (0)
; #define PG8_WAIT_V(n) asm volatile("s_waitcnt vmcnt(" #n ")" ::: "memory")
; #define PG8_WAIT_L(n) asm volatile("s_waitcnt lgkmcnt(" #n ")" ::: "memory")
; #define PG8_BAR __builtin_amdgcn_s_barrier()
; #define PG8_SCHED __builtin_amdgcn_sched_barrier(0)
; template <class Epi, class Sched, bool ALIGN_EPI = false, bool SP2 = false>
; __device__ __forceinline__ void gemm_phase(PG8_LAS unsigned char* lds, const Gemm g, const Sched& S, const Epi& E, const int tid_arg) {
;     ...
;             PG8_WAIT_V(8); PG8_WAIT_L(0); PG8_BAR; PG8_MMA(1, 0, At, B0); PG8_MMA(1, 1, At, B1); PG8_BAR; PG8_SCHED;
;             PG8_LDB(B0, 1, 0); PG8_LDB(B1, 1, 1); PG8_SCHED; PG8_LDA(At, 1, 0); PG8_STAGE(PG8_SA(0, 1), a2 + hstep, voffA);
;             PG8_WAIT_V(8); PG8_WAIT_L(0); PG8_BAR; PG8_MMA(0, 0, At, B0); PG8_MMA(0, 1, At, B1); PG8_BAR; PG8_SCHED;
	s_setprio 1
	s_waitcnt lgkmcnt(0)
	v_mfma_f32_16x16x32_bf16 v[64:67], v[156:159], v[214:217], v[64:67]
	v_mfma_f32_16x16x32_bf16 v[60:63], v[170:173], v[214:217], v[60:63]
	v_mfma_f32_16x16x32_bf16 v[48:51], v[156:159], v[222:225], v[48:51]
	v_mfma_f32_16x16x32_bf16 v[44:47], v[170:173], v[222:225], v[44:47]
	v_mfma_f32_16x16x32_bf16 v[32:35], v[156:159], v[230:233], v[32:35]
	v_mfma_f32_16x16x32_bf16 v[28:31], v[170:173], v[230:233], v[28:31]
	v_mfma_f32_16x16x32_bf16 v[16:19], v[156:159], v[238:241], v[16:19]
	v_mfma_f32_16x16x32_bf16 v[12:15], v[170:173], v[238:241], v[12:15]
	v_mfma_f32_16x16x32_bf16 v[64:67], v[160:163], v[218:221], v[64:67]
	v_mfma_f32_16x16x32_bf16 v[60:63], v[174:177], v[218:221], v[60:63]
	v_mfma_f32_16x16x32_bf16 v[48:51], v[160:163], v[226:229], v[48:51]
	v_mfma_f32_16x16x32_bf16 v[44:47], v[174:177], v[226:229], v[44:47]
	v_mfma_f32_16x16x32_bf16 v[32:35], v[160:163], v[234:237], v[32:35]
	v_mfma_f32_16x16x32_bf16 v[28:31], v[174:177], v[234:237], v[28:31]
	v_mfma_f32_16x16x32_bf16 v[16:19], v[160:163], v[242:245], v[16:19]
	v_mfma_f32_16x16x32_bf16 v[12:15], v[174:177], v[242:245], v[12:15]
	s_setprio 0
	s_setprio 1
	v_mfma_f32_16x16x32_bf16 v[56:59], v[182:185], v[214:217], v[56:59]
	v_mfma_f32_16x16x32_bf16 v[52:55], v[190:193], v[214:217], v[52:55]
	v_mfma_f32_16x16x32_bf16 v[40:43], v[182:185], v[222:225], v[40:43]
	v_mfma_f32_16x16x32_bf16 v[36:39], v[190:193], v[222:225], v[36:39]
	v_mfma_f32_16x16x32_bf16 v[24:27], v[182:185], v[230:233], v[24:27]
	v_mfma_f32_16x16x32_bf16 v[20:23], v[190:193], v[230:233], v[20:23]
	v_mfma_f32_16x16x32_bf16 v[8:11], v[182:185], v[238:241], v[8:11]
	v_mfma_f32_16x16x32_bf16 v[4:7], v[190:193], v[238:241], v[4:7]
	v_mfma_f32_16x16x32_bf16 v[56:59], v[186:189], v[218:221], v[56:59]
	v_mfma_f32_16x16x32_bf16 v[52:55], v[210:213], v[218:221], v[52:55]
	v_mfma_f32_16x16x32_bf16 v[40:43], v[186:189], v[226:229], v[40:43]
	v_mfma_f32_16x16x32_bf16 v[36:39], v[210:213], v[226:229], v[36:39]
	v_mfma_f32_16x16x32_bf16 v[24:27], v[186:189], v[234:237], v[24:27]
	v_mfma_f32_16x16x32_bf16 v[20:23], v[210:213], v[234:237], v[20:23]
	v_mfma_f32_16x16x32_bf16 v[8:11], v[186:189], v[242:245], v[8:11]
	v_mfma_f32_16x16x32_bf16 v[4:7], v[210:213], v[242:245], v[4:7]
	s_setprio 0
	s_barrier
	s_add_i32 s41, 0, 0x18000
	v_add_u32_e32 v2, s41, v167
	s_add_i32 s42, 0, 0x1c000
	ds_read_b128 v[156:159], v2
	ds_read_b128 v[160:163], v2 offset:1024
	ds_read_b128 v[170:173], v2 offset:2048
	ds_read_b128 v[174:177], v2 offset:3072
	v_add_u32_e32 v2, s42, v167
	ds_read_b128 v[182:185], v2
	ds_read_b128 v[186:189], v2 offset:1024
	ds_read_b128 v[190:193], v2 offset:2048
	ds_read_b128 v[210:213], v2 offset:3072
	s_add_u32 s38, s38, 0x40000
	s_addc_u32 s39, s39, 0
	s_mov_b32 m0, s57
	v_lshl_add_u64 v[248:249], s[38:39], 0, v[132:133]
	ds_read_b128 v[214:217], v169 offset:32768
	ds_read_b128 v[218:221], v169 offset:33792
	ds_read_b128 v[222:225], v169 offset:34816
	ds_read_b128 v[226:229], v169 offset:35840
	ds_read_b128 v[230:233], v169 offset:36864
	ds_read_b128 v[234:237], v169 offset:37888
	ds_read_b128 v[238:241], v169 offset:38912
	ds_read_b128 v[242:245], v169 offset:39936
	global_load_lds_dwordx4 v[248:249], off
	v_lshl_add_u64 v[248:249], s[38:39], 0, v[136:137]
	s_mov_b32 m0, s58
	s_nop 0
	global_load_lds_dwordx4 v[248:249], off
	s_waitcnt vmcnt(8)
	s_waitcnt lgkmcnt(0)
	s_barrier
	s_setprio 1
	s_waitcnt lgkmcnt(0)
	v_mfma_f32_16x16x32_bf16 v[128:131], v[156:159], v[214:217], v[128:131]
	v_mfma_f32_16x16x32_bf16 v[124:127], v[170:173], v[214:217], v[124:127]
	v_mfma_f32_16x16x32_bf16 v[112:115], v[156:159], v[222:225], v[112:115]
	v_mfma_f32_16x16x32_bf16 v[108:111], v[170:173], v[222:225], v[108:111]
	v_mfma_f32_16x16x32_bf16 v[96:99], v[156:159], v[230:233], v[96:99]
	v_mfma_f32_16x16x32_bf16 v[92:95], v[170:173], v[230:233], v[92:95]
	v_mfma_f32_16x16x32_bf16 v[80:83], v[156:159], v[238:241], v[80:83]
	v_mfma_f32_16x16x32_bf16 v[76:79], v[170:173], v[238:241], v[76:79]
	v_mfma_f32_16x16x32_bf16 v[128:131], v[160:163], v[218:221], v[128:131]
	v_mfma_f32_16x16x32_bf16 v[124:127], v[174:177], v[218:221], v[124:127]
	v_mfma_f32_16x16x32_bf16 v[112:115], v[160:163], v[226:229], v[112:115]
	v_mfma_f32_16x16x32_bf16 v[108:111], v[174:177], v[226:229], v[108:111]
	v_mfma_f32_16x16x32_bf16 v[96:99], v[160:163], v[234:237], v[96:99]
	v_mfma_f32_16x16x32_bf16 v[92:95], v[174:177], v[234:237], v[92:95]
	v_mfma_f32_16x16x32_bf16 v[80:83], v[160:163], v[242:245], v[80:83]
	v_mfma_f32_16x16x32_bf16 v[76:79], v[174:177], v[242:245], v[76:79]
	s_setprio 0
	s_setprio 1
	v_mfma_f32_16x16x32_bf16 v[120:123], v[182:185], v[214:217], v[120:123]
	v_mfma_f32_16x16x32_bf16 v[116:119], v[190:193], v[214:217], v[116:119]
	v_mfma_f32_16x16x32_bf16 v[104:107], v[182:185], v[222:225], v[104:107]
	v_mfma_f32_16x16x32_bf16 v[100:103], v[190:193], v[222:225], v[100:103]
	v_mfma_f32_16x16x32_bf16 v[88:91], v[182:185], v[230:233], v[88:91]
	v_mfma_f32_16x16x32_bf16 v[84:87], v[190:193], v[230:233], v[84:87]
	v_mfma_f32_16x16x32_bf16 v[72:75], v[182:185], v[238:241], v[72:75]
	v_mfma_f32_16x16x32_bf16 v[68:71], v[190:193], v[238:241], v[68:71]
	v_mfma_f32_16x16x32_bf16 v[120:123], v[186:189], v[218:221], v[120:123]
	v_mfma_f32_16x16x32_bf16 v[116:119], v[210:213], v[218:221], v[116:119]
	v_mfma_f32_16x16x32_bf16 v[104:107], v[186:189], v[226:229], v[104:107]
	v_mfma_f32_16x16x32_bf16 v[100:103], v[210:213], v[226:229], v[100:103]
	v_mfma_f32_16x16x32_bf16 v[88:91], v[186:189], v[234:237], v[88:91]
	v_mfma_f32_16x16x32_bf16 v[84:87], v[210:213], v[234:237], v[84:87]
	v_mfma_f32_16x16x32_bf16 v[72:75], v[186:189], v[242:245], v[72:75]
	v_mfma_f32_16x16x32_bf16 v[68:71], v[210:213], v[242:245], v[68:71]
	s_setprio 0
	s_barrier
; #define PG8_STAGE(bufoff, gbase, voff) do { _Pragma("unroll") for (int _i = 0; _i < 2; ++_i) \
;         __builtin_amdgcn_global_load_lds((const unsigned*)((const char*)(gbase) + (voff)[_i]), (PG8_LAS unsigned*)(lds + (bufoff) + ldsw + _i * 8192), 16, 0, 0); } while (0)
; #define PG8_LDA(dst, b, h) do { _Pragma("unroll") for (int m = 0; m < 4; ++m) _Pragma("unroll") for (int k = 0; k < 2; ++k) dst[m][k] = *(const PG8_LAS bf16x8*)(lds + PG8_SA(b, h) + aoff + m * 2048 + k * 1024); } while (0)
; #define PG8_MMA(ai, bj, At, Bt) do { __builtin_amdgcn_s_setprio(1); _Pragma("unroll") for (int m = 0; m < 4; ++m) _Pragma("unroll") for (int n = 0; n < 2; ++n) _Pragma("unroll") for (int k = 0; k < 2; ++k) \
;         acc[ai][bj][m][n] = __builtin_amdgcn_mfma_f32_16x16x32_bf16(Bt[n][k], At[m][k], acc[ai][bj][m][n], 0, 0, 0); __builtin_amdgcn_s_setprio(0); } while (0)
; #define PG8_WAIT_V(n) asm volatile("s_waitcnt vmcnt(" #n ")" ::: "memory")
; #define PG8_WAIT_L(n) asm volatile("s_waitcnt lgkmcnt(" #n ")" ::: "memory")
; #define PG8_BAR __builtin_amdgcn_s_barrier()
; #define PG8_SCHED __builtin_amdgcn_sched_barrier(0)
; __device__ __forceinline__ float rstd_from_ss(const float* ssrow, int fq) {
;     const f32x4 a = ((const f32x4*)ssrow)[fq];
; template <class Epi, class Sched, bool ALIGN_EPI = false, bool SP2 = false>
; __device__ __forceinline__ void gemm_phase(PG8_LAS unsigned char* lds, const Gemm g, const Sched& S, const Epi& E, const int tid_arg) {
;     ...
;             PG8_WAIT_V(8); PG8_WAIT_L(0); PG8_BAR; PG8_MMA(0, 0, At, B0); PG8_MMA(0, 1, At, B1); PG8_BAR; PG8_SCHED;
;             PG8_LDA(At, 1, 1); PG8_STAGE(PG8_SB(1, 0), b3, voffB); PG8_STAGE(PG8_SB(1, 1), b3 + hstep, voffB); PG8_STAGE(PG8_SA(1, 0), a3, voffA);
;             PG8_WAIT_V(8); PG8_WAIT_L(0); PG8_BAR; PG8_MMA(1, 0, At, B0); PG8_MMA(1, 1, At, B1); PG8_BAR; PG8_SCHED;
	s_add_i32 s38, s41, s54
	v_lshl_add_u64 v[164:165], v[164:165], 0, s[76:77]
	s_mov_b32 m0, s38
	ds_read_b128 v[214:217], v169 offset:49152
	ds_read_b128 v[218:221], v169 offset:50176
	ds_read_b128 v[222:225], v169 offset:51200
	ds_read_b128 v[226:229], v169 offset:52224
	ds_read_b128 v[230:233], v169 offset:53248
	ds_read_b128 v[234:237], v169 offset:54272
	ds_read_b128 v[238:241], v169 offset:55296
	ds_read_b128 v[242:245], v169 offset:56320
	global_load_lds_dwordx4 v[164:165], off
	s_add_i32 m0, s38, 0x2000
	s_add_u32 s36, s36, 0x40080
	v_lshl_add_u64 v[164:165], v[178:179], 0, s[76:77]
	s_addc_u32 s37, s37, 0
	s_add_i32 s38, s42, s54
	global_load_lds_dwordx4 v[164:165], off
	v_lshl_add_u64 v[164:165], s[36:37], 0, v[134:135]
	s_mov_b32 m0, s38
	s_nop 0
	global_load_lds_dwordx4 v[164:165], off
	v_lshl_add_u64 v[164:165], s[36:37], 0, v[138:139]
	s_add_i32 m0, s38, 0x2000
	s_nop 0
	global_load_lds_dwordx4 v[164:165], off
	v_lshl_add_u64 v[164:165], v[194:195], 0, s[76:77]
	s_mov_b32 m0, s61
	s_nop 0
	global_load_lds_dwordx4 v[164:165], off
	v_lshl_add_u64 v[164:165], v[246:247], 0, s[76:77]
	s_mov_b32 m0, s62
	s_nop 0
	global_load_lds_dwordx4 v[164:165], off
	s_waitcnt vmcnt(8)
	s_waitcnt lgkmcnt(0)
	s_barrier
	s_setprio 1
	s_waitcnt lgkmcnt(0)
	v_mfma_f32_16x16x32_bf16 v[64:67], v[156:159], v[214:217], v[64:67]
	v_mfma_f32_16x16x32_bf16 v[60:63], v[170:173], v[214:217], v[60:63]
	v_mfma_f32_16x16x32_bf16 v[48:51], v[156:159], v[222:225], v[48:51]
	v_mfma_f32_16x16x32_bf16 v[44:47], v[170:173], v[222:225], v[44:47]
	v_mfma_f32_16x16x32_bf16 v[32:35], v[156:159], v[230:233], v[32:35]
	v_mfma_f32_16x16x32_bf16 v[28:31], v[170:173], v[230:233], v[28:31]
	v_mfma_f32_16x16x32_bf16 v[16:19], v[156:159], v[238:241], v[16:19]
	v_mfma_f32_16x16x32_bf16 v[12:15], v[170:173], v[238:241], v[12:15]
	v_mfma_f32_16x16x32_bf16 v[64:67], v[160:163], v[218:221], v[64:67]
	v_mfma_f32_16x16x32_bf16 v[60:63], v[174:177], v[218:221], v[60:63]
	v_mfma_f32_16x16x32_bf16 v[48:51], v[160:163], v[226:229], v[48:51]
	v_mfma_f32_16x16x32_bf16 v[44:47], v[174:177], v[226:229], v[44:47]
	v_mfma_f32_16x16x32_bf16 v[32:35], v[160:163], v[234:237], v[32:35]
	v_mfma_f32_16x16x32_bf16 v[28:31], v[174:177], v[234:237], v[28:31]
	v_mfma_f32_16x16x32_bf16 v[16:19], v[160:163], v[242:245], v[16:19]
	v_mfma_f32_16x16x32_bf16 v[12:15], v[174:177], v[242:245], v[12:15]
	s_setprio 0
	s_setprio 1
	v_mfma_f32_16x16x32_bf16 v[56:59], v[182:185], v[214:217], v[56:59]
	v_mfma_f32_16x16x32_bf16 v[52:55], v[190:193], v[214:217], v[52:55]
	v_mfma_f32_16x16x32_bf16 v[40:43], v[182:185], v[222:225], v[40:43]
	v_mfma_f32_16x16x32_bf16 v[36:39], v[190:193], v[222:225], v[36:39]
	v_mfma_f32_16x16x32_bf16 v[24:27], v[182:185], v[230:233], v[24:27]
	v_mfma_f32_16x16x32_bf16 v[20:23], v[190:193], v[230:233], v[20:23]
	v_mfma_f32_16x16x32_bf16 v[8:11], v[182:185], v[238:241], v[8:11]
	v_mfma_f32_16x16x32_bf16 v[4:7], v[190:193], v[238:241], v[4:7]
	v_mfma_f32_16x16x32_bf16 v[56:59], v[186:189], v[218:221], v[56:59]
	v_mfma_f32_16x16x32_bf16 v[52:55], v[210:213], v[218:221], v[52:55]
	v_mfma_f32_16x16x32_bf16 v[40:43], v[186:189], v[226:229], v[40:43]
	v_mfma_f32_16x16x32_bf16 v[36:39], v[210:213], v[226:229], v[36:39]
	v_mfma_f32_16x16x32_bf16 v[24:27], v[186:189], v[234:237], v[24:27]
	v_mfma_f32_16x16x32_bf16 v[20:23], v[210:213], v[234:237], v[20:23]
	v_mfma_f32_16x16x32_bf16 v[8:11], v[186:189], v[242:245], v[8:11]
	v_mfma_f32_16x16x32_bf16 v[4:7], v[210:213], v[242:245], v[4:7]
	s_setprio 0
	s_barrier
	s_add_i32 s40, s40, 2
	s_add_u32 s14, s14, 0x100
	s_addc_u32 s15, s15, 0
	s_add_u32 s27, s27, 0x100
	s_addc_u32 s29, s29, 0
	s_cmp_gt_u32 s40, 13
	s_cbranch_scc0 .LBB0_363
	s_lshl_b32 s40, s12, 8
	v_add_u32_e32 v170, s40, v166
	v_ashrrev_i32_e32 v171, 31, v170
	v_lshlrev_b64 v[172:173], 6, v[170:171]
	s_mov_b64 s[40:41], 0x2000
	v_lshl_add_u64 v[172:173], v[146:147], 0, v[172:173]
	v_lshl_add_u64 v[174:175], v[172:173], 0, s[40:41]
	global_load_dwordx4 v[210:213], v[172:173], off
	global_load_dwordx4 v[214:217], v[172:173], off offset:1024
	global_load_dwordx4 v[218:221], v[172:173], off offset:2048
	global_load_dwordx4 v[222:225], v[172:173], off offset:3072
	global_load_dwordx4 v[226:229], v[174:175], off
	global_load_dwordx4 v[230:233], v[174:175], off offset:1024
	global_load_dwordx4 v[234:237], v[174:175], off offset:2048
	global_load_dwordx4 v[238:241], v[174:175], off offset:3072
	s_and_b64 vcc, exec, s[22:23]
	s_cbranch_vccz .LBB0_449
	s_barrier
	s_cmp_gt_i32 s10, 23
	s_mov_b64 s[14:15], -1
	s_cbranch_scc1 .LBB0_450

; __device__ __forceinline__ float rstd_from_ss(const float* ssrow, int fq) {
;     const f32x4 a = ((const f32x4*)ssrow)[fq];
;     float s = (a[0] + a[1]) + (a[2] + a[3]);
;     s += __shfl_xor(s, 16); s += __shfl_xor(s, 32);
;     return rsqrtf(s * (1.0f / 1024.0f) + 1e-6f);
; }
;     __device__ __forceinline__ void operator()(const f32x4 (&acc)[2][2][4][2], const Unit& u, int wr, int wc, int fr, int fq) const {
;     ...
;                 int row = lrow0 + ai * HALF + m * 16; asm volatile("" : "+v"(row));
;                 const float rs = rstd_from_ss(SS + (size_t)row * 16, fq);
.LBB0_374:
	v_add_u32_e32 v170, s7, v166
	v_ashrrev_i32_e32 v171, 31, v170
	s_mov_b64 s[40:41], 0x2000
	v_add_u32_e32 v2, s6, v168
	v_lshl_add_u64 v[156:157], v[2:3], 1, s[14:15]
	v_mad_i64_i32 v[160:161], s[42:43], s36, v170, 0
	v_lshl_add_u64 v[158:159], v[2:3], 2, s[12:13]
	v_lshl_add_u64 v[162:163], s[38:39], 0, v[170:171]
	v_lshl_add_u64 v[156:157], v[160:161], 1, v[156:157]
	v_lshlrev_b64 v[162:163], 12, v[162:163]
	v_lshlrev_b64 v[160:161], 6, v[170:171]
	v_lshl_add_u64 v[158:159], v[158:159], 0, v[162:163]
	v_lshl_add_u64 v[160:161], v[148:149], 0, v[160:161]
	v_lshl_add_u64 v[162:163], v[160:161], 0, s[40:41]
	s_waitcnt vmcnt(4)
	v_add_f32_e32 v210, v211, v210
	v_add_f32_e32 v214, v215, v214
	v_add_f32_e32 v218, v219, v218
	v_add_f32_e32 v222, v223, v222
	v_add_f32_e32 v212, v212, v213
	v_add_f32_e32 v216, v216, v217
	v_add_f32_e32 v220, v220, v221
	v_add_f32_e32 v224, v224, v225
	v_add_f32_e32 v210, v210, v212
	v_add_f32_e32 v214, v214, v216
	v_add_f32_e32 v218, v218, v220
	v_add_f32_e32 v222, v222, v224
	ds_bpermute_b32 v211, v199, v210
	ds_bpermute_b32 v215, v199, v214
	ds_bpermute_b32 v219, v199, v218
	ds_bpermute_b32 v223, v199, v222
	s_waitcnt vmcnt(0)
	v_add_f32_e32 v226, v227, v226
	v_add_f32_e32 v230, v231, v230
	v_add_f32_e32 v234, v235, v234
	v_add_f32_e32 v238, v239, v238
	v_add_f32_e32 v228, v228, v229
	v_add_f32_e32 v232, v232, v233
	v_add_f32_e32 v236, v236, v237
	v_add_f32_e32 v240, v240, v241
	v_add_f32_e32 v226, v226, v228
	v_add_f32_e32 v230, v230, v232
	v_add_f32_e32 v234, v234, v236
	v_add_f32_e32 v238, v238, v240
	ds_bpermute_b32 v227, v199, v226
	ds_bpermute_b32 v231, v199, v230
	ds_bpermute_b32 v235, v199, v234
	ds_bpermute_b32 v239, v199, v238
	s_waitcnt lgkmcnt(4)
	v_add_f32_e32 v210, v210, v211
	v_add_f32_e32 v214, v214, v215
	v_add_f32_e32 v218, v218, v219
	v_add_f32_e32 v222, v222, v223
	ds_bpermute_b32 v211, v200, v210
	ds_bpermute_b32 v215, v200, v214
	ds_bpermute_b32 v219, v200, v218
	ds_bpermute_b32 v223, v200, v222
	s_waitcnt lgkmcnt(4)
	v_add_f32_e32 v226, v226, v227
	v_add_f32_e32 v230, v230, v231
	v_add_f32_e32 v234, v234, v235
	v_add_f32_e32 v238, v238, v239
	ds_bpermute_b32 v227, v200, v226
	ds_bpermute_b32 v231, v200, v230
	ds_bpermute_b32 v235, v200, v234
	ds_bpermute_b32 v239, v200, v238
	s_waitcnt lgkmcnt(4)
	v_add_f32_e32 v210, v210, v211
	v_add_f32_e32 v214, v214, v215
	v_add_f32_e32 v218, v218, v219
	v_add_f32_e32 v222, v222, v223
	v_fmamk_f32 v210, v210, 0x3a800000, v140
	v_fmamk_f32 v214, v214, 0x3a800000, v140
	v_fmamk_f32 v218, v218, 0x3a800000, v140
	v_fmamk_f32 v222, v222, 0x3a800000, v140
	v_cmp_gt_f32_e64 vcc, s92, v210
	v_cmp_gt_f32_e64 s[6:7], s92, v214
	v_cmp_gt_f32_e64 s[40:41], s92, v218
	v_cmp_gt_f32_e64 s[42:43], s92, v222
	v_mul_f32_e32 v211, 0x4b800000, v210
	v_mul_f32_e32 v215, 0x4b800000, v214
	v_mul_f32_e32 v219, 0x4b800000, v218
	v_mul_f32_e32 v223, 0x4b800000, v222
	v_cndmask_b32_e64 v210, v210, v211, vcc
	v_cndmask_b32_e64 v214, v214, v215, s[6:7]
	v_cndmask_b32_e64 v218, v218, v219, s[40:41]
	v_cndmask_b32_e64 v222, v222, v223, s[42:43]
	v_rsq_f32_e32 v210, v210
	v_rsq_f32_e32 v214, v214
	v_rsq_f32_e32 v218, v218
	v_rsq_f32_e32 v222, v222
	v_mul_f32_e32 v211, 0x45800000, v210
	v_mul_f32_e32 v215, 0x45800000, v214
	v_mul_f32_e32 v219, 0x45800000, v218
	v_mul_f32_e32 v223, 0x45800000, v222
	v_cndmask_b32_e64 v210, v210, v211, vcc
	v_cndmask_b32_e64 v214, v214, v215, s[6:7]
	v_cndmask_b32_e64 v218, v218, v219, s[40:41]
	v_cndmask_b32_e64 v222, v222, v223, s[42:43]
	s_waitcnt lgkmcnt(0)
	v_add_f32_e32 v226, v226, v227
	v_add_f32_e32 v230, v230, v231
	v_add_f32_e32 v234, v234, v235
	v_add_f32_e32 v238, v238, v239
	v_fmamk_f32 v226, v226, 0x3a800000, v140
	v_fmamk_f32 v230, v230, 0x3a800000, v140
	v_fmamk_f32 v234, v234, 0x3a800000, v140
	v_fmamk_f32 v238, v238, 0x3a800000, v140
	v_cmp_gt_f32_e64 vcc, s92, v226
	v_cmp_gt_f32_e64 s[6:7], s92, v230
	v_cmp_gt_f32_e64 s[40:41], s92, v234
	v_cmp_gt_f32_e64 s[42:43], s92, v238
	v_mul_f32_e32 v227, 0x4b800000, v226
	v_mul_f32_e32 v231, 0x4b800000, v230
	v_mul_f32_e32 v235, 0x4b800000, v234
	v_mul_f32_e32 v239, 0x4b800000, v238
	v_cndmask_b32_e64 v226, v226, v227, vcc
	v_cndmask_b32_e64 v230, v230, v231, s[6:7]
	v_cndmask_b32_e64 v234, v234, v235, s[40:41]
	v_cndmask_b32_e64 v238, v238, v239, s[42:43]
	v_rsq_f32_e32 v226, v226
	v_rsq_f32_e32 v230, v230
	v_rsq_f32_e32 v234, v234
	v_rsq_f32_e32 v238, v238
	v_mul_f32_e32 v227, 0x45800000, v226
	v_mul_f32_e32 v231, 0x45800000, v230
	v_mul_f32_e32 v235, 0x45800000, v234
	v_mul_f32_e32 v239, 0x45800000, v238
	v_cndmask_b32_e64 v226, v226, v227, vcc
	v_cndmask_b32_e64 v230, v230, v231, s[6:7]
	v_cndmask_b32_e64 v234, v234, v235, s[40:41]
	v_cndmask_b32_e64 v238, v238, v239, s[42:43]
	s_cmp_gt_i32 s10, 31
	s_cbranch_scc1 .Lp3e_fa
	s_lshl_b32 s40, s36, 5
	s_mov_b32 s41, 0
	s_mul_i32 s42, s36, 0xa0
	s_mov_b32 s43, 0
	s_cmp_lg_u64 s[12:13], 0
	s_cbranch_scc1 .Lp3e_kv
; __device__ __forceinline__ unsigned cvt_pk_bf16(float lo, float hi) { f32x2_cv v = {lo, hi}; bf16x2_cv b = __builtin_convertvector(v, bf16x2_cv); return __builtin_bit_cast(unsigned, b); }
;     __device__ __forceinline__ void operator()(const f32x4 (&acc)[2][2][4][2], const Unit& u, int wr, int wc, int fr, int fq) const {
;     ...
;                 int row = lrow0 + ai * HALF + m * 16; asm volatile("" : "+v"(row));
;                 const float rs = rstd_from_ss(SS + (size_t)row * 16, fq);
;                 if (pn < 32) {
; #pragma unroll
;                     for (int bj = 0; bj < 2; ++bj) {
;                         const f32x4 v0 = acc[ai][bj][m][0] * rs, v1 = acc[ai][bj][m][1] * rs;
;                         u32x4 w; w.x = cvt_pk_bf16(v0[0], v0[1]); w.y = cvt_pk_bf16(v0[2], v0[3]); w.z = cvt_pk_bf16(v1[0], v1[1]); w.w = cvt_pk_bf16(v1[2], v1[3]);
;                         if (pn >= 24) __builtin_nontemporal_store(w, (u32x4*)(dst + (size_t)row * ldc + col0 + bj * HALF)); else *(u32x4*)(dst + (size_t)row * ldc + col0 + bj * HALF) = w;
	v_pk_mul_f32 v[128:129], v[128:129], v[210:211] op_sel_hi:[1,0]
	v_pk_mul_f32 v[130:131], v[130:131], v[210:211] op_sel_hi:[1,0]
	v_pk_mul_f32 v[124:125], v[124:125], v[210:211] op_sel_hi:[1,0]
	v_pk_mul_f32 v[126:127], v[126:127], v[210:211] op_sel_hi:[1,0]
	v_cvt_pk_bf16_f32 v182, v128, v129
	v_cvt_pk_bf16_f32 v183, v130, v131
	v_cvt_pk_bf16_f32 v184, v124, v125
	v_cvt_pk_bf16_f32 v185, v126, v127
	global_store_dwordx4 v[156:157], v[182:185], off
	v_pk_mul_f32 v[120:121], v[120:121], v[210:211] op_sel_hi:[1,0]
	v_pk_mul_f32 v[122:123], v[122:123], v[210:211] op_sel_hi:[1,0]
	v_pk_mul_f32 v[116:117], v[116:117], v[210:211] op_sel_hi:[1,0]
	v_pk_mul_f32 v[118:119], v[118:119], v[210:211] op_sel_hi:[1,0]
	v_cvt_pk_bf16_f32 v186, v120, v121
	v_cvt_pk_bf16_f32 v187, v122, v123
	v_cvt_pk_bf16_f32 v188, v116, v117
	v_cvt_pk_bf16_f32 v189, v118, v119
	global_store_dwordx4 v[156:157], v[186:189], off offset:256
	v_lshl_add_u64 v[156:157], v[156:157], 0, s[40:41]
	v_pk_mul_f32 v[112:113], v[112:113], v[214:215] op_sel_hi:[1,0]
	v_pk_mul_f32 v[114:115], v[114:115], v[214:215] op_sel_hi:[1,0]
	v_pk_mul_f32 v[108:109], v[108:109], v[214:215] op_sel_hi:[1,0]
	v_pk_mul_f32 v[110:111], v[110:111], v[214:215] op_sel_hi:[1,0]
	v_cvt_pk_bf16_f32 v190, v112, v113
	v_cvt_pk_bf16_f32 v191, v114, v115
	v_cvt_pk_bf16_f32 v192, v108, v109
	v_cvt_pk_bf16_f32 v193, v110, v111
	global_store_dwordx4 v[156:157], v[190:193], off
	v_pk_mul_f32 v[104:105], v[104:105], v[214:215] op_sel_hi:[1,0]
	v_pk_mul_f32 v[106:107], v[106:107], v[214:215] op_sel_hi:[1,0]
	v_pk_mul_f32 v[100:101], v[100:101], v[214:215] op_sel_hi:[1,0]
	v_pk_mul_f32 v[102:103], v[102:103], v[214:215] op_sel_hi:[1,0]
	v_cvt_pk_bf16_f32 v242, v104, v105
	v_cvt_pk_bf16_f32 v243, v106, v107
	v_cvt_pk_bf16_f32 v244, v100, v101
	v_cvt_pk_bf16_f32 v245, v102, v103
	global_store_dwordx4 v[156:157], v[242:245], off offset:256
	v_lshl_add_u64 v[156:157], v[156:157], 0, s[40:41]
	v_pk_mul_f32 v[96:97], v[96:97], v[218:219] op_sel_hi:[1,0]
	v_pk_mul_f32 v[98:99], v[98:99], v[218:219] op_sel_hi:[1,0]
	v_pk_mul_f32 v[92:93], v[92:93], v[218:219] op_sel_hi:[1,0]
	v_pk_mul_f32 v[94:95], v[94:95], v[218:219] op_sel_hi:[1,0]
	v_cvt_pk_bf16_f32 v182, v96, v97
	v_cvt_pk_bf16_f32 v183, v98, v99
	v_cvt_pk_bf16_f32 v184, v92, v93
	v_cvt_pk_bf16_f32 v185, v94, v95
	global_store_dwordx4 v[156:157], v[182:185], off
	v_pk_mul_f32 v[88:89], v[88:89], v[218:219] op_sel_hi:[1,0]
	v_pk_mul_f32 v[90:91], v[90:91], v[218:219] op_sel_hi:[1,0]
	v_pk_mul_f32 v[84:85], v[84:85], v[218:219] op_sel_hi:[1,0]
	v_pk_mul_f32 v[86:87], v[86:87], v[218:219] op_sel_hi:[1,0]
	v_cvt_pk_bf16_f32 v186, v88, v89
	v_cvt_pk_bf16_f32 v187, v90, v91
	v_cvt_pk_bf16_f32 v188, v84, v85
	v_cvt_pk_bf16_f32 v189, v86, v87
	global_store_dwordx4 v[156:157], v[186:189], off offset:256
	v_lshl_add_u64 v[156:157], v[156:157], 0, s[40:41]
	v_pk_mul_f32 v[80:81], v[80:81], v[222:223] op_sel_hi:[1,0]
	v_pk_mul_f32 v[82:83], v[82:83], v[222:223] op_sel_hi:[1,0]
	v_pk_mul_f32 v[76:77], v[76:77], v[222:223] op_sel_hi:[1,0]
	v_pk_mul_f32 v[78:79], v[78:79], v[222:223] op_sel_hi:[1,0]
	v_cvt_pk_bf16_f32 v190, v80, v81
	v_cvt_pk_bf16_f32 v191, v82, v83
	v_cvt_pk_bf16_f32 v192, v76, v77
	v_cvt_pk_bf16_f32 v193, v78, v79
	global_store_dwordx4 v[156:157], v[190:193], off
	v_pk_mul_f32 v[72:73], v[72:73], v[222:223] op_sel_hi:[1,0]
	v_pk_mul_f32 v[74:75], v[74:75], v[222:223] op_sel_hi:[1,0]
	v_pk_mul_f32 v[68:69], v[68:69], v[222:223] op_sel_hi:[1,0]
	v_pk_mul_f32 v[70:71], v[70:71], v[222:223] op_sel_hi:[1,0]
	v_cvt_pk_bf16_f32 v242, v72, v73
	v_cvt_pk_bf16_f32 v243, v74, v75
	v_cvt_pk_bf16_f32 v244, v68, v69
	v_cvt_pk_bf16_f32 v245, v70, v71
	global_store_dwordx4 v[156:157], v[242:245], off offset:256
; __device__ __forceinline__ unsigned cvt_pk_bf16(float lo, float hi) { f32x2_cv v = {lo, hi}; bf16x2_cv b = __builtin_convertvector(v, bf16x2_cv); return __builtin_bit_cast(unsigned, b); }
;     __device__ __forceinline__ void operator()(const f32x4 (&acc)[2][2][4][2], const Unit& u, int wr, int wc, int fr, int fq) const {
;     ...
;                 int row = lrow0 + ai * HALF + m * 16; asm volatile("" : "+v"(row));
;                 const float rs = rstd_from_ss(SS + (size_t)row * 16, fq);
;                 if (pn < 32) {
; #pragma unroll
;                     for (int bj = 0; bj < 2; ++bj) {
;                         const f32x4 v0 = acc[ai][bj][m][0] * rs, v1 = acc[ai][bj][m][1] * rs;
;                         u32x4 w; w.x = cvt_pk_bf16(v0[0], v0[1]); w.y = cvt_pk_bf16(v0[2], v0[3]); w.z = cvt_pk_bf16(v1[0], v1[1]); w.w = cvt_pk_bf16(v1[2], v1[3]);
;                         if (pn >= 24) __builtin_nontemporal_store(w, (u32x4*)(dst + (size_t)row * ldc + col0 + bj * HALF)); else *(u32x4*)(dst + (size_t)row * ldc + col0 + bj * HALF) = w;
	v_lshl_add_u64 v[156:157], v[156:157], 0, s[42:43]
	v_pk_mul_f32 v[64:65], v[64:65], v[226:227] op_sel_hi:[1,0]
	v_pk_mul_f32 v[66:67], v[66:67], v[226:227] op_sel_hi:[1,0]
	v_pk_mul_f32 v[60:61], v[60:61], v[226:227] op_sel_hi:[1,0]
	v_pk_mul_f32 v[62:63], v[62:63], v[226:227] op_sel_hi:[1,0]
	v_cvt_pk_bf16_f32 v182, v64, v65
	v_cvt_pk_bf16_f32 v183, v66, v67
	v_cvt_pk_bf16_f32 v184, v60, v61
	v_cvt_pk_bf16_f32 v185, v62, v63
	global_store_dwordx4 v[156:157], v[182:185], off
	v_pk_mul_f32 v[56:57], v[56:57], v[226:227] op_sel_hi:[1,0]
	v_pk_mul_f32 v[58:59], v[58:59], v[226:227] op_sel_hi:[1,0]
	v_pk_mul_f32 v[52:53], v[52:53], v[226:227] op_sel_hi:[1,0]
	v_pk_mul_f32 v[54:55], v[54:55], v[226:227] op_sel_hi:[1,0]
	v_cvt_pk_bf16_f32 v186, v56, v57
	v_cvt_pk_bf16_f32 v187, v58, v59
	v_cvt_pk_bf16_f32 v188, v52, v53
	v_cvt_pk_bf16_f32 v189, v54, v55
	global_store_dwordx4 v[156:157], v[186:189], off offset:256
	v_lshl_add_u64 v[156:157], v[156:157], 0, s[40:41]
	v_pk_mul_f32 v[48:49], v[48:49], v[230:231] op_sel_hi:[1,0]
	v_pk_mul_f32 v[50:51], v[50:51], v[230:231] op_sel_hi:[1,0]
	v_pk_mul_f32 v[44:45], v[44:45], v[230:231] op_sel_hi:[1,0]
	v_pk_mul_f32 v[46:47], v[46:47], v[230:231] op_sel_hi:[1,0]
	v_cvt_pk_bf16_f32 v190, v48, v49
	v_cvt_pk_bf16_f32 v191, v50, v51
	v_cvt_pk_bf16_f32 v192, v44, v45
	v_cvt_pk_bf16_f32 v193, v46, v47
	global_store_dwordx4 v[156:157], v[190:193], off
	v_pk_mul_f32 v[40:41], v[40:41], v[230:231] op_sel_hi:[1,0]
	v_pk_mul_f32 v[42:43], v[42:43], v[230:231] op_sel_hi:[1,0]
	v_pk_mul_f32 v[36:37], v[36:37], v[230:231] op_sel_hi:[1,0]
	v_pk_mul_f32 v[38:39], v[38:39], v[230:231] op_sel_hi:[1,0]
	v_cvt_pk_bf16_f32 v242, v40, v41
	v_cvt_pk_bf16_f32 v243, v42, v43
	v_cvt_pk_bf16_f32 v244, v36, v37
	v_cvt_pk_bf16_f32 v245, v38, v39
	global_store_dwordx4 v[156:157], v[242:245], off offset:256
	v_lshl_add_u64 v[156:157], v[156:157], 0, s[40:41]
	v_pk_mul_f32 v[32:33], v[32:33], v[234:235] op_sel_hi:[1,0]
	v_pk_mul_f32 v[34:35], v[34:35], v[234:235] op_sel_hi:[1,0]
	v_pk_mul_f32 v[28:29], v[28:29], v[234:235] op_sel_hi:[1,0]
	v_pk_mul_f32 v[30:31], v[30:31], v[234:235] op_sel_hi:[1,0]
	v_cvt_pk_bf16_f32 v182, v32, v33
	v_cvt_pk_bf16_f32 v183, v34, v35
	v_cvt_pk_bf16_f32 v184, v28, v29
	v_cvt_pk_bf16_f32 v185, v30, v31
	global_store_dwordx4 v[156:157], v[182:185], off
	v_pk_mul_f32 v[24:25], v[24:25], v[234:235] op_sel_hi:[1,0]
	v_pk_mul_f32 v[26:27], v[26:27], v[234:235] op_sel_hi:[1,0]
	v_pk_mul_f32 v[20:21], v[20:21], v[234:235] op_sel_hi:[1,0]
	v_pk_mul_f32 v[22:23], v[22:23], v[234:235] op_sel_hi:[1,0]
	v_cvt_pk_bf16_f32 v186, v24, v25
	v_cvt_pk_bf16_f32 v187, v26, v27
	v_cvt_pk_bf16_f32 v188, v20, v21
	v_cvt_pk_bf16_f32 v189, v22, v23
	global_store_dwordx4 v[156:157], v[186:189], off offset:256
	v_lshl_add_u64 v[156:157], v[156:157], 0, s[40:41]
	v_pk_mul_f32 v[16:17], v[16:17], v[238:239] op_sel_hi:[1,0]
	v_pk_mul_f32 v[18:19], v[18:19], v[238:239] op_sel_hi:[1,0]
	v_pk_mul_f32 v[12:13], v[12:13], v[238:239] op_sel_hi:[1,0]
	v_pk_mul_f32 v[14:15], v[14:15], v[238:239] op_sel_hi:[1,0]
	v_cvt_pk_bf16_f32 v190, v16, v17
	v_cvt_pk_bf16_f32 v191, v18, v19
	v_cvt_pk_bf16_f32 v192, v12, v13
	v_cvt_pk_bf16_f32 v193, v14, v15
	global_store_dwordx4 v[156:157], v[190:193], off
	v_pk_mul_f32 v[8:9], v[8:9], v[238:239] op_sel_hi:[1,0]
	v_pk_mul_f32 v[10:11], v[10:11], v[238:239] op_sel_hi:[1,0]
	v_pk_mul_f32 v[4:5], v[4:5], v[238:239] op_sel_hi:[1,0]
	v_pk_mul_f32 v[6:7], v[6:7], v[238:239] op_sel_hi:[1,0]
	v_cvt_pk_bf16_f32 v242, v8, v9
	v_cvt_pk_bf16_f32 v243, v10, v11
	v_cvt_pk_bf16_f32 v244, v4, v5
	v_cvt_pk_bf16_f32 v245, v6, v7
	global_store_dwordx4 v[156:157], v[242:245], off offset:256
	s_branch .LBB0_446

; #define PG8_WAIT_V(n) asm volatile("s_waitcnt vmcnt(" #n ")" ::: "memory")
; #define PG8_BAR __builtin_amdgcn_s_barrier()
; template <class Epi, class Sched, bool ALIGN_EPI = false, bool SP2 = false>
; __device__ __forceinline__ void gemm_phase(PG8_LAS unsigned char* lds, const Gemm g, const Sched& S, const Epi& E, const int tid_arg) {
;     ...
;     PG8_WAIT_V(0);
;     if constexpr (!ALIGN_EPI) { if (wr == 0) PG8_BAR; }
;     PG8_BAR;
.LBB0_451:
	s_waitcnt vmcnt(0)
	s_barrier
	s_nop 0
	s_nop 0
	s_nop 0
	s_nop 0
	s_nop 0
	s_nop 0
	s_nop 0
	s_nop 0
	s_nop 0
	s_nop 0
	s_nop 0
	s_nop 0
	s_nop 0
	s_nop 0
	s_nop 0
	s_nop 0
	s_nop 0
	s_nop 0
	s_nop 0
	s_nop 0
	s_nop 0
	s_nop 0
	s_nop 0
	s_nop 0
	s_nop 0
	s_nop 0
	s_nop 0
	s_nop 0
	s_nop 0
	s_nop 0
	s_nop 0
	s_nop 0
	s_nop 0
	s_nop 0
	s_nop 0
	s_nop 0
	s_nop 0
	s_nop 0
	s_nop 0
	s_nop 0
	s_nop 0
	s_nop 0
	s_nop 0
	s_nop 0
	s_nop 0
	s_nop 0
	s_nop 0
	s_nop 0
	s_nop 0
	s_nop 0
	s_nop 0
	s_nop 0
	s_nop 0
	s_nop 0
	s_nop 0
	s_nop 0
	s_nop 0
	s_nop 0
	s_nop 0
